# conv module depthwise FIR: 992 v_fmac_f32 -> 496 v_pk_fma_f32 streamed over y pairs (same tap order per output), weights loaded before the barrier
# speedup vs baseline: 1.0001x; 1.0001x over previous
; __device__ __forceinline__ void conv_unit(Ctx& F, const bf16* P, bf16* O, int seq_row0, int seq_len, int t0, const float* wdw, const float* bdw, const float* lng, const float* lnb) {
;     ...
;     __syncthreads();
;     const int c = tid & 255, hf = tid >> 8;
;     float w[31];
; #pragma unroll
;     for (int k = 0; k < 31; ++k) w[k] = wdw[k * 256 + c];
;     const float bb = bdw[c];
;     float outv[32];
; #pragma unroll
;     for (int tt = 0; tt < 32; ++tt) { float a = bb; const float* yp = y + (hf * 32 + tt) * 256 + c;
; #pragma unroll
;         for (int k = 0; k < 31; ++k) a += w[k] * yp[k * 256];
;         outv[tt] = a; }
.LBB0_635:
	s_or_b64 exec, exec, s[0:1]
	v_lshlrev_b32_e32 v81, 2, v80
	v_and_b32_e32 v204, 0x3fc, v81
	global_load_dword v32, v204, s[16:17]
	global_load_dword v33, v204, s[16:17] offset:1024
	global_load_dword v34, v204, s[16:17] offset:2048
	global_load_dword v35, v204, s[16:17] offset:3072
	v_add_u32_e32 v81, 0x1000, v204
	global_load_dword v36, v81, s[16:17]
	global_load_dword v37, v81, s[16:17] offset:1024
	global_load_dword v38, v81, s[16:17] offset:2048
	global_load_dword v39, v81, s[16:17] offset:3072
	v_add_u32_e32 v81, 0x2000, v204
	global_load_dword v40, v81, s[16:17]
	global_load_dword v41, v81, s[16:17] offset:1024
	global_load_dword v42, v81, s[16:17] offset:2048
	global_load_dword v43, v81, s[16:17] offset:3072
	v_add_u32_e32 v81, 0x3000, v204
	global_load_dword v44, v81, s[16:17]
	global_load_dword v45, v81, s[16:17] offset:1024
	global_load_dword v46, v81, s[16:17] offset:2048
	global_load_dword v47, v81, s[16:17] offset:3072
	v_add_u32_e32 v81, 0x4000, v204
	global_load_dword v48, v81, s[16:17]
	global_load_dword v49, v81, s[16:17] offset:1024
	global_load_dword v50, v81, s[16:17] offset:2048
	global_load_dword v51, v81, s[16:17] offset:3072
	v_add_u32_e32 v81, 0x5000, v204
	global_load_dword v52, v81, s[16:17]
	global_load_dword v53, v81, s[16:17] offset:1024
	global_load_dword v54, v81, s[16:17] offset:2048
	global_load_dword v55, v81, s[16:17] offset:3072
	v_add_u32_e32 v81, 0x6000, v204
	global_load_dword v56, v81, s[16:17]
	global_load_dword v57, v81, s[16:17] offset:1024
	global_load_dword v58, v81, s[16:17] offset:2048
	global_load_dword v59, v81, s[16:17] offset:3072
	v_add_u32_e32 v81, 0x7000, v204
	global_load_dword v60, v81, s[16:17]
	global_load_dword v61, v81, s[16:17] offset:1024
	global_load_dword v62, v81, s[16:17] offset:2048
	global_load_dword v64, v204, s[18:19]
	s_waitcnt lgkmcnt(0)
	s_barrier
	v_lshlrev_b32_e32 v96, 7, v80
	v_and_b32_e32 v96, 0xffff8000, v96
	v_add_u32_e32 v96, v96, v204
	s_and_b32 s0, s40, 0x7fffff00
	s_and_b32 s1, s39, 0xc0
	s_ashr_i32 s3, s44, 3
	s_and_b32 s4, s3, -8
	s_or_b32 s0, s0, s1
	s_add_i32 s0, s0, s4
	s_lshl_b32 s3, s3, 10
	s_add_i32 s0, s0, 0x8000
	s_and_b32 s3, s3, 0xffffe000
	s_ashr_i32 s1, s0, 31
	s_add_i32 s3, s3, 0
	s_lshl_b64 s[0:1], s[0:1], 11
	s_add_u32 s0, s37, s0
	s_addc_u32 s1, s38, s1
	s_mov_b32 s2, 0
	v_cmp_lt_i32_e32 vcc, v237, v236
	ds_read2st64_b32 v[66:67], v96 offset1:4
	ds_read2st64_b32 v[68:69], v96 offset0:4 offset1:8
	ds_read2st64_b32 v[70:71], v96 offset0:8 offset1:12
	ds_read2st64_b32 v[72:73], v96 offset0:12 offset1:16
	ds_read2st64_b32 v[74:75], v96 offset0:16 offset1:20
	ds_read2st64_b32 v[76:77], v96 offset0:20 offset1:24
	s_waitcnt vmcnt(0)
	ds_read2st64_b32 v[78:79], v96 offset0:24 offset1:28
	s_waitcnt lgkmcnt(6)
	v_pk_fma_f32 v[0:1], v[66:67], v[32:33], v[64:65] op_sel_hi:[1,0,0]
	ds_read2st64_b32 v[82:83], v96 offset0:28 offset1:32
	s_waitcnt lgkmcnt(6)
	v_pk_fma_f32 v[0:1], v[68:69], v[32:33], v[0:1] op_sel:[0,1,0] op_sel_hi:[1,1,1]
	ds_read2st64_b32 v[84:85], v96 offset0:32 offset1:36
	s_waitcnt lgkmcnt(6)
	v_pk_fma_f32 v[0:1], v[70:71], v[34:35], v[0:1] op_sel_hi:[1,0,1]
	v_pk_fma_f32 v[2:3], v[70:71], v[32:33], v[64:65] op_sel_hi:[1,0,0]
	ds_read2st64_b32 v[86:87], v96 offset0:36 offset1:40
	s_waitcnt lgkmcnt(6)
	v_pk_fma_f32 v[0:1], v[72:73], v[34:35], v[0:1] op_sel:[0,1,0] op_sel_hi:[1,1,1]
	v_pk_fma_f32 v[2:3], v[72:73], v[32:33], v[2:3] op_sel:[0,1,0] op_sel_hi:[1,1,1]
	ds_read2st64_b32 v[88:89], v96 offset0:40 offset1:44
	s_waitcnt lgkmcnt(6)
	v_pk_fma_f32 v[0:1], v[74:75], v[36:37], v[0:1] op_sel_hi:[1,0,1]
	v_pk_fma_f32 v[2:3], v[74:75], v[34:35], v[2:3] op_sel_hi:[1,0,1]
	v_pk_fma_f32 v[4:5], v[74:75], v[32:33], v[64:65] op_sel_hi:[1,0,0]
	ds_read2st64_b32 v[90:91], v96 offset0:44 offset1:48
	s_waitcnt lgkmcnt(6)
	v_pk_fma_f32 v[0:1], v[76:77], v[36:37], v[0:1] op_sel:[0,1,0] op_sel_hi:[1,1,1]
	v_pk_fma_f32 v[2:3], v[76:77], v[34:35], v[2:3] op_sel:[0,1,0] op_sel_hi:[1,1,1]
	v_pk_fma_f32 v[4:5], v[76:77], v[32:33], v[4:5] op_sel:[0,1,0] op_sel_hi:[1,1,1]
	ds_read2st64_b32 v[92:93], v96 offset0:48 offset1:52
	s_waitcnt lgkmcnt(6)
	v_pk_fma_f32 v[0:1], v[78:79], v[38:39], v[0:1] op_sel_hi:[1,0,1]
	v_pk_fma_f32 v[2:3], v[78:79], v[36:37], v[2:3] op_sel_hi:[1,0,1]
	v_pk_fma_f32 v[4:5], v[78:79], v[34:35], v[4:5] op_sel_hi:[1,0,1]
	v_pk_fma_f32 v[6:7], v[78:79], v[32:33], v[64:65] op_sel_hi:[1,0,0]
	ds_read2st64_b32 v[94:95], v96 offset0:52 offset1:56
	s_waitcnt lgkmcnt(6)
	v_pk_fma_f32 v[0:1], v[82:83], v[38:39], v[0:1] op_sel:[0,1,0] op_sel_hi:[1,1,1]
	v_pk_fma_f32 v[2:3], v[82:83], v[36:37], v[2:3] op_sel:[0,1,0] op_sel_hi:[1,1,1]
	v_pk_fma_f32 v[4:5], v[82:83], v[34:35], v[4:5] op_sel:[0,1,0] op_sel_hi:[1,1,1]
	v_pk_fma_f32 v[6:7], v[82:83], v[32:33], v[6:7] op_sel:[0,1,0] op_sel_hi:[1,1,1]
	ds_read2st64_b32 v[66:67], v96 offset0:56 offset1:60
	s_waitcnt lgkmcnt(6)
	v_pk_fma_f32 v[0:1], v[84:85], v[40:41], v[0:1] op_sel_hi:[1,0,1]
	v_pk_fma_f32 v[2:3], v[84:85], v[38:39], v[2:3] op_sel_hi:[1,0,1]
	v_pk_fma_f32 v[4:5], v[84:85], v[36:37], v[4:5] op_sel_hi:[1,0,1]
	v_pk_fma_f32 v[6:7], v[84:85], v[34:35], v[6:7] op_sel_hi:[1,0,1]
	v_pk_fma_f32 v[8:9], v[84:85], v[32:33], v[64:65] op_sel_hi:[1,0,0]
	ds_read2st64_b32 v[68:69], v96 offset0:60 offset1:64
	s_waitcnt lgkmcnt(6)
	v_pk_fma_f32 v[0:1], v[86:87], v[40:41], v[0:1] op_sel:[0,1,0] op_sel_hi:[1,1,1]
	v_pk_fma_f32 v[2:3], v[86:87], v[38:39], v[2:3] op_sel:[0,1,0] op_sel_hi:[1,1,1]
	v_pk_fma_f32 v[4:5], v[86:87], v[36:37], v[4:5] op_sel:[0,1,0] op_sel_hi:[1,1,1]
	v_pk_fma_f32 v[6:7], v[86:87], v[34:35], v[6:7] op_sel:[0,1,0] op_sel_hi:[1,1,1]
	v_pk_fma_f32 v[8:9], v[86:87], v[32:33], v[8:9] op_sel:[0,1,0] op_sel_hi:[1,1,1]
	ds_read2st64_b32 v[70:71], v96 offset0:64 offset1:68
	s_waitcnt lgkmcnt(6)
; __device__ __forceinline__ void conv_unit(Ctx& F, const bf16* P, bf16* O, int seq_row0, int seq_len, int t0, const float* wdw, const float* bdw, const float* lng, const float* lnb) {
;     ...
;     for (int tt = 0; tt < 32; ++tt) { float a = bb; const float* yp = y + (hf * 32 + tt) * 256 + c;
; #pragma unroll
;         for (int k = 0; k < 31; ++k) a += w[k] * yp[k * 256];
;         outv[tt] = a; }
	v_pk_fma_f32 v[0:1], v[88:89], v[42:43], v[0:1] op_sel_hi:[1,0,1]
	v_pk_fma_f32 v[2:3], v[88:89], v[40:41], v[2:3] op_sel_hi:[1,0,1]
	v_pk_fma_f32 v[4:5], v[88:89], v[38:39], v[4:5] op_sel_hi:[1,0,1]
	v_pk_fma_f32 v[6:7], v[88:89], v[36:37], v[6:7] op_sel_hi:[1,0,1]
	v_pk_fma_f32 v[8:9], v[88:89], v[34:35], v[8:9] op_sel_hi:[1,0,1]
	v_pk_fma_f32 v[10:11], v[88:89], v[32:33], v[64:65] op_sel_hi:[1,0,0]
	ds_read2st64_b32 v[72:73], v96 offset0:68 offset1:72
	s_waitcnt lgkmcnt(6)
	v_pk_fma_f32 v[0:1], v[90:91], v[42:43], v[0:1] op_sel:[0,1,0] op_sel_hi:[1,1,1]
	v_pk_fma_f32 v[2:3], v[90:91], v[40:41], v[2:3] op_sel:[0,1,0] op_sel_hi:[1,1,1]
	v_pk_fma_f32 v[4:5], v[90:91], v[38:39], v[4:5] op_sel:[0,1,0] op_sel_hi:[1,1,1]
	v_pk_fma_f32 v[6:7], v[90:91], v[36:37], v[6:7] op_sel:[0,1,0] op_sel_hi:[1,1,1]
	v_pk_fma_f32 v[8:9], v[90:91], v[34:35], v[8:9] op_sel:[0,1,0] op_sel_hi:[1,1,1]
	v_pk_fma_f32 v[10:11], v[90:91], v[32:33], v[10:11] op_sel:[0,1,0] op_sel_hi:[1,1,1]
	ds_read2st64_b32 v[74:75], v96 offset0:72 offset1:76
	s_waitcnt lgkmcnt(6)
	v_pk_fma_f32 v[0:1], v[92:93], v[44:45], v[0:1] op_sel_hi:[1,0,1]
	v_pk_fma_f32 v[2:3], v[92:93], v[42:43], v[2:3] op_sel_hi:[1,0,1]
	v_pk_fma_f32 v[4:5], v[92:93], v[40:41], v[4:5] op_sel_hi:[1,0,1]
	v_pk_fma_f32 v[6:7], v[92:93], v[38:39], v[6:7] op_sel_hi:[1,0,1]
	v_pk_fma_f32 v[8:9], v[92:93], v[36:37], v[8:9] op_sel_hi:[1,0,1]
	v_pk_fma_f32 v[10:11], v[92:93], v[34:35], v[10:11] op_sel_hi:[1,0,1]
	v_pk_fma_f32 v[12:13], v[92:93], v[32:33], v[64:65] op_sel_hi:[1,0,0]
	ds_read2st64_b32 v[76:77], v96 offset0:76 offset1:80
	s_waitcnt lgkmcnt(6)
	v_pk_fma_f32 v[0:1], v[94:95], v[44:45], v[0:1] op_sel:[0,1,0] op_sel_hi:[1,1,1]
	v_pk_fma_f32 v[2:3], v[94:95], v[42:43], v[2:3] op_sel:[0,1,0] op_sel_hi:[1,1,1]
	v_pk_fma_f32 v[4:5], v[94:95], v[40:41], v[4:5] op_sel:[0,1,0] op_sel_hi:[1,1,1]
	v_pk_fma_f32 v[6:7], v[94:95], v[38:39], v[6:7] op_sel:[0,1,0] op_sel_hi:[1,1,1]
	v_pk_fma_f32 v[8:9], v[94:95], v[36:37], v[8:9] op_sel:[0,1,0] op_sel_hi:[1,1,1]
	v_pk_fma_f32 v[10:11], v[94:95], v[34:35], v[10:11] op_sel:[0,1,0] op_sel_hi:[1,1,1]
	v_pk_fma_f32 v[12:13], v[94:95], v[32:33], v[12:13] op_sel:[0,1,0] op_sel_hi:[1,1,1]
	ds_read2st64_b32 v[78:79], v96 offset0:80 offset1:84
	s_waitcnt lgkmcnt(6)
	v_pk_fma_f32 v[0:1], v[66:67], v[46:47], v[0:1] op_sel_hi:[1,0,1]
	v_pk_fma_f32 v[2:3], v[66:67], v[44:45], v[2:3] op_sel_hi:[1,0,1]
	v_pk_fma_f32 v[4:5], v[66:67], v[42:43], v[4:5] op_sel_hi:[1,0,1]
	v_pk_fma_f32 v[6:7], v[66:67], v[40:41], v[6:7] op_sel_hi:[1,0,1]
	v_pk_fma_f32 v[8:9], v[66:67], v[38:39], v[8:9] op_sel_hi:[1,0,1]
	v_pk_fma_f32 v[10:11], v[66:67], v[36:37], v[10:11] op_sel_hi:[1,0,1]
	v_pk_fma_f32 v[12:13], v[66:67], v[34:35], v[12:13] op_sel_hi:[1,0,1]
	v_pk_fma_f32 v[14:15], v[66:67], v[32:33], v[64:65] op_sel_hi:[1,0,0]
	ds_read2st64_b32 v[82:83], v96 offset0:84 offset1:88
	s_waitcnt lgkmcnt(6)
	v_pk_fma_f32 v[0:1], v[68:69], v[46:47], v[0:1] op_sel:[0,1,0] op_sel_hi:[1,1,1]
	v_pk_fma_f32 v[2:3], v[68:69], v[44:45], v[2:3] op_sel:[0,1,0] op_sel_hi:[1,1,1]
	v_pk_fma_f32 v[4:5], v[68:69], v[42:43], v[4:5] op_sel:[0,1,0] op_sel_hi:[1,1,1]
	v_pk_fma_f32 v[6:7], v[68:69], v[40:41], v[6:7] op_sel:[0,1,0] op_sel_hi:[1,1,1]
	v_pk_fma_f32 v[8:9], v[68:69], v[38:39], v[8:9] op_sel:[0,1,0] op_sel_hi:[1,1,1]
	v_pk_fma_f32 v[10:11], v[68:69], v[36:37], v[10:11] op_sel:[0,1,0] op_sel_hi:[1,1,1]
	v_pk_fma_f32 v[12:13], v[68:69], v[34:35], v[12:13] op_sel:[0,1,0] op_sel_hi:[1,1,1]
	v_pk_fma_f32 v[14:15], v[68:69], v[32:33], v[14:15] op_sel:[0,1,0] op_sel_hi:[1,1,1]
	ds_read2st64_b32 v[84:85], v96 offset0:88 offset1:92
	s_waitcnt lgkmcnt(6)
	v_pk_fma_f32 v[0:1], v[70:71], v[48:49], v[0:1] op_sel_hi:[1,0,1]
	v_pk_fma_f32 v[2:3], v[70:71], v[46:47], v[2:3] op_sel_hi:[1,0,1]
	v_pk_fma_f32 v[4:5], v[70:71], v[44:45], v[4:5] op_sel_hi:[1,0,1]
	v_pk_fma_f32 v[6:7], v[70:71], v[42:43], v[6:7] op_sel_hi:[1,0,1]
	v_pk_fma_f32 v[8:9], v[70:71], v[40:41], v[8:9] op_sel_hi:[1,0,1]
	v_pk_fma_f32 v[10:11], v[70:71], v[38:39], v[10:11] op_sel_hi:[1,0,1]
	v_pk_fma_f32 v[12:13], v[70:71], v[36:37], v[12:13] op_sel_hi:[1,0,1]
	v_pk_fma_f32 v[14:15], v[70:71], v[34:35], v[14:15] op_sel_hi:[1,0,1]
	v_pk_fma_f32 v[16:17], v[70:71], v[32:33], v[64:65] op_sel_hi:[1,0,0]
	ds_read2st64_b32 v[86:87], v96 offset0:92 offset1:96
	s_waitcnt lgkmcnt(6)
	v_pk_fma_f32 v[0:1], v[72:73], v[48:49], v[0:1] op_sel:[0,1,0] op_sel_hi:[1,1,1]
	v_pk_fma_f32 v[2:3], v[72:73], v[46:47], v[2:3] op_sel:[0,1,0] op_sel_hi:[1,1,1]
	v_pk_fma_f32 v[4:5], v[72:73], v[44:45], v[4:5] op_sel:[0,1,0] op_sel_hi:[1,1,1]
	v_pk_fma_f32 v[6:7], v[72:73], v[42:43], v[6:7] op_sel:[0,1,0] op_sel_hi:[1,1,1]
	v_pk_fma_f32 v[8:9], v[72:73], v[40:41], v[8:9] op_sel:[0,1,0] op_sel_hi:[1,1,1]
	v_pk_fma_f32 v[10:11], v[72:73], v[38:39], v[10:11] op_sel:[0,1,0] op_sel_hi:[1,1,1]
	v_pk_fma_f32 v[12:13], v[72:73], v[36:37], v[12:13] op_sel:[0,1,0] op_sel_hi:[1,1,1]
	v_pk_fma_f32 v[14:15], v[72:73], v[34:35], v[14:15] op_sel:[0,1,0] op_sel_hi:[1,1,1]
	v_pk_fma_f32 v[16:17], v[72:73], v[32:33], v[16:17] op_sel:[0,1,0] op_sel_hi:[1,1,1]
	ds_read2st64_b32 v[88:89], v96 offset0:96 offset1:100
	s_waitcnt lgkmcnt(6)
	v_pk_fma_f32 v[0:1], v[74:75], v[50:51], v[0:1] op_sel_hi:[1,0,1]
	v_pk_fma_f32 v[2:3], v[74:75], v[48:49], v[2:3] op_sel_hi:[1,0,1]
	v_pk_fma_f32 v[4:5], v[74:75], v[46:47], v[4:5] op_sel_hi:[1,0,1]
	v_pk_fma_f32 v[6:7], v[74:75], v[44:45], v[6:7] op_sel_hi:[1,0,1]
	v_pk_fma_f32 v[8:9], v[74:75], v[42:43], v[8:9] op_sel_hi:[1,0,1]
	v_pk_fma_f32 v[10:11], v[74:75], v[40:41], v[10:11] op_sel_hi:[1,0,1]
	v_pk_fma_f32 v[12:13], v[74:75], v[38:39], v[12:13] op_sel_hi:[1,0,1]
	v_pk_fma_f32 v[14:15], v[74:75], v[36:37], v[14:15] op_sel_hi:[1,0,1]
	v_pk_fma_f32 v[16:17], v[74:75], v[34:35], v[16:17] op_sel_hi:[1,0,1]
	v_pk_fma_f32 v[18:19], v[74:75], v[32:33], v[64:65] op_sel_hi:[1,0,0]
	ds_read2st64_b32 v[90:91], v96 offset0:100 offset1:104
	s_waitcnt lgkmcnt(6)
; __device__ __forceinline__ void conv_unit(Ctx& F, const bf16* P, bf16* O, int seq_row0, int seq_len, int t0, const float* wdw, const float* bdw, const float* lng, const float* lnb) {
;     ...
;     for (int tt = 0; tt < 32; ++tt) { float a = bb; const float* yp = y + (hf * 32 + tt) * 256 + c;
; #pragma unroll
;         for (int k = 0; k < 31; ++k) a += w[k] * yp[k * 256];
;         outv[tt] = a; }
	v_pk_fma_f32 v[0:1], v[76:77], v[50:51], v[0:1] op_sel:[0,1,0] op_sel_hi:[1,1,1]
	v_pk_fma_f32 v[2:3], v[76:77], v[48:49], v[2:3] op_sel:[0,1,0] op_sel_hi:[1,1,1]
	v_pk_fma_f32 v[4:5], v[76:77], v[46:47], v[4:5] op_sel:[0,1,0] op_sel_hi:[1,1,1]
	v_pk_fma_f32 v[6:7], v[76:77], v[44:45], v[6:7] op_sel:[0,1,0] op_sel_hi:[1,1,1]
	v_pk_fma_f32 v[8:9], v[76:77], v[42:43], v[8:9] op_sel:[0,1,0] op_sel_hi:[1,1,1]
	v_pk_fma_f32 v[10:11], v[76:77], v[40:41], v[10:11] op_sel:[0,1,0] op_sel_hi:[1,1,1]
	v_pk_fma_f32 v[12:13], v[76:77], v[38:39], v[12:13] op_sel:[0,1,0] op_sel_hi:[1,1,1]
	v_pk_fma_f32 v[14:15], v[76:77], v[36:37], v[14:15] op_sel:[0,1,0] op_sel_hi:[1,1,1]
	v_pk_fma_f32 v[16:17], v[76:77], v[34:35], v[16:17] op_sel:[0,1,0] op_sel_hi:[1,1,1]
	v_pk_fma_f32 v[18:19], v[76:77], v[32:33], v[18:19] op_sel:[0,1,0] op_sel_hi:[1,1,1]
	ds_read2st64_b32 v[92:93], v96 offset0:104 offset1:108
	s_waitcnt lgkmcnt(6)
	v_pk_fma_f32 v[0:1], v[78:79], v[52:53], v[0:1] op_sel_hi:[1,0,1]
	v_pk_fma_f32 v[2:3], v[78:79], v[50:51], v[2:3] op_sel_hi:[1,0,1]
	v_pk_fma_f32 v[4:5], v[78:79], v[48:49], v[4:5] op_sel_hi:[1,0,1]
	v_pk_fma_f32 v[6:7], v[78:79], v[46:47], v[6:7] op_sel_hi:[1,0,1]
	v_pk_fma_f32 v[8:9], v[78:79], v[44:45], v[8:9] op_sel_hi:[1,0,1]
	v_pk_fma_f32 v[10:11], v[78:79], v[42:43], v[10:11] op_sel_hi:[1,0,1]
	v_pk_fma_f32 v[12:13], v[78:79], v[40:41], v[12:13] op_sel_hi:[1,0,1]
	v_pk_fma_f32 v[14:15], v[78:79], v[38:39], v[14:15] op_sel_hi:[1,0,1]
	v_pk_fma_f32 v[16:17], v[78:79], v[36:37], v[16:17] op_sel_hi:[1,0,1]
	v_pk_fma_f32 v[18:19], v[78:79], v[34:35], v[18:19] op_sel_hi:[1,0,1]
	v_pk_fma_f32 v[20:21], v[78:79], v[32:33], v[64:65] op_sel_hi:[1,0,0]
	ds_read2st64_b32 v[94:95], v96 offset0:108 offset1:112
	s_waitcnt lgkmcnt(6)
	v_pk_fma_f32 v[0:1], v[82:83], v[52:53], v[0:1] op_sel:[0,1,0] op_sel_hi:[1,1,1]
	v_pk_fma_f32 v[2:3], v[82:83], v[50:51], v[2:3] op_sel:[0,1,0] op_sel_hi:[1,1,1]
	v_pk_fma_f32 v[4:5], v[82:83], v[48:49], v[4:5] op_sel:[0,1,0] op_sel_hi:[1,1,1]
	v_pk_fma_f32 v[6:7], v[82:83], v[46:47], v[6:7] op_sel:[0,1,0] op_sel_hi:[1,1,1]
	v_pk_fma_f32 v[8:9], v[82:83], v[44:45], v[8:9] op_sel:[0,1,0] op_sel_hi:[1,1,1]
	v_pk_fma_f32 v[10:11], v[82:83], v[42:43], v[10:11] op_sel:[0,1,0] op_sel_hi:[1,1,1]
	v_pk_fma_f32 v[12:13], v[82:83], v[40:41], v[12:13] op_sel:[0,1,0] op_sel_hi:[1,1,1]
	v_pk_fma_f32 v[14:15], v[82:83], v[38:39], v[14:15] op_sel:[0,1,0] op_sel_hi:[1,1,1]
	v_pk_fma_f32 v[16:17], v[82:83], v[36:37], v[16:17] op_sel:[0,1,0] op_sel_hi:[1,1,1]
	v_pk_fma_f32 v[18:19], v[82:83], v[34:35], v[18:19] op_sel:[0,1,0] op_sel_hi:[1,1,1]
	v_pk_fma_f32 v[20:21], v[82:83], v[32:33], v[20:21] op_sel:[0,1,0] op_sel_hi:[1,1,1]
	ds_read2st64_b32 v[66:67], v96 offset0:112 offset1:116
	s_waitcnt lgkmcnt(6)
	v_pk_fma_f32 v[0:1], v[84:85], v[54:55], v[0:1] op_sel_hi:[1,0,1]
	v_pk_fma_f32 v[2:3], v[84:85], v[52:53], v[2:3] op_sel_hi:[1,0,1]
	v_pk_fma_f32 v[4:5], v[84:85], v[50:51], v[4:5] op_sel_hi:[1,0,1]
	v_pk_fma_f32 v[6:7], v[84:85], v[48:49], v[6:7] op_sel_hi:[1,0,1]
	v_pk_fma_f32 v[8:9], v[84:85], v[46:47], v[8:9] op_sel_hi:[1,0,1]
	v_pk_fma_f32 v[10:11], v[84:85], v[44:45], v[10:11] op_sel_hi:[1,0,1]
	v_pk_fma_f32 v[12:13], v[84:85], v[42:43], v[12:13] op_sel_hi:[1,0,1]
	v_pk_fma_f32 v[14:15], v[84:85], v[40:41], v[14:15] op_sel_hi:[1,0,1]
	v_pk_fma_f32 v[16:17], v[84:85], v[38:39], v[16:17] op_sel_hi:[1,0,1]
	v_pk_fma_f32 v[18:19], v[84:85], v[36:37], v[18:19] op_sel_hi:[1,0,1]
	v_pk_fma_f32 v[20:21], v[84:85], v[34:35], v[20:21] op_sel_hi:[1,0,1]
	v_pk_fma_f32 v[22:23], v[84:85], v[32:33], v[64:65] op_sel_hi:[1,0,0]
	ds_read2st64_b32 v[68:69], v96 offset0:116 offset1:120
	s_waitcnt lgkmcnt(6)
	v_pk_fma_f32 v[0:1], v[86:87], v[54:55], v[0:1] op_sel:[0,1,0] op_sel_hi:[1,1,1]
	v_pk_fma_f32 v[2:3], v[86:87], v[52:53], v[2:3] op_sel:[0,1,0] op_sel_hi:[1,1,1]
	v_pk_fma_f32 v[4:5], v[86:87], v[50:51], v[4:5] op_sel:[0,1,0] op_sel_hi:[1,1,1]
	v_pk_fma_f32 v[6:7], v[86:87], v[48:49], v[6:7] op_sel:[0,1,0] op_sel_hi:[1,1,1]
	v_pk_fma_f32 v[8:9], v[86:87], v[46:47], v[8:9] op_sel:[0,1,0] op_sel_hi:[1,1,1]
	v_pk_fma_f32 v[10:11], v[86:87], v[44:45], v[10:11] op_sel:[0,1,0] op_sel_hi:[1,1,1]
	v_pk_fma_f32 v[12:13], v[86:87], v[42:43], v[12:13] op_sel:[0,1,0] op_sel_hi:[1,1,1]
	v_pk_fma_f32 v[14:15], v[86:87], v[40:41], v[14:15] op_sel:[0,1,0] op_sel_hi:[1,1,1]
	v_pk_fma_f32 v[16:17], v[86:87], v[38:39], v[16:17] op_sel:[0,1,0] op_sel_hi:[1,1,1]
	v_pk_fma_f32 v[18:19], v[86:87], v[36:37], v[18:19] op_sel:[0,1,0] op_sel_hi:[1,1,1]
	v_pk_fma_f32 v[20:21], v[86:87], v[34:35], v[20:21] op_sel:[0,1,0] op_sel_hi:[1,1,1]
	v_pk_fma_f32 v[22:23], v[86:87], v[32:33], v[22:23] op_sel:[0,1,0] op_sel_hi:[1,1,1]
	ds_read2st64_b32 v[70:71], v96 offset0:120 offset1:124
	s_waitcnt lgkmcnt(6)
	v_pk_fma_f32 v[0:1], v[88:89], v[56:57], v[0:1] op_sel_hi:[1,0,1]
	v_pk_fma_f32 v[2:3], v[88:89], v[54:55], v[2:3] op_sel_hi:[1,0,1]
	v_pk_fma_f32 v[4:5], v[88:89], v[52:53], v[4:5] op_sel_hi:[1,0,1]
	v_pk_fma_f32 v[6:7], v[88:89], v[50:51], v[6:7] op_sel_hi:[1,0,1]
	v_pk_fma_f32 v[8:9], v[88:89], v[48:49], v[8:9] op_sel_hi:[1,0,1]
	v_pk_fma_f32 v[10:11], v[88:89], v[46:47], v[10:11] op_sel_hi:[1,0,1]
	v_pk_fma_f32 v[12:13], v[88:89], v[44:45], v[12:13] op_sel_hi:[1,0,1]
	v_pk_fma_f32 v[14:15], v[88:89], v[42:43], v[14:15] op_sel_hi:[1,0,1]
	v_pk_fma_f32 v[16:17], v[88:89], v[40:41], v[16:17] op_sel_hi:[1,0,1]
	v_pk_fma_f32 v[18:19], v[88:89], v[38:39], v[18:19] op_sel_hi:[1,0,1]
	v_pk_fma_f32 v[20:21], v[88:89], v[36:37], v[20:21] op_sel_hi:[1,0,1]
	v_pk_fma_f32 v[22:23], v[88:89], v[34:35], v[22:23] op_sel_hi:[1,0,1]
	v_pk_fma_f32 v[24:25], v[88:89], v[32:33], v[64:65] op_sel_hi:[1,0,0]
	ds_read2st64_b32 v[72:73], v96 offset0:124 offset1:128
	s_waitcnt lgkmcnt(6)
; __device__ __forceinline__ void conv_unit(Ctx& F, const bf16* P, bf16* O, int seq_row0, int seq_len, int t0, const float* wdw, const float* bdw, const float* lng, const float* lnb) {
;     ...
;     for (int tt = 0; tt < 32; ++tt) { float a = bb; const float* yp = y + (hf * 32 + tt) * 256 + c;
; #pragma unroll
;         for (int k = 0; k < 31; ++k) a += w[k] * yp[k * 256];
;         outv[tt] = a; }
	v_pk_fma_f32 v[0:1], v[90:91], v[56:57], v[0:1] op_sel:[0,1,0] op_sel_hi:[1,1,1]
	v_pk_fma_f32 v[2:3], v[90:91], v[54:55], v[2:3] op_sel:[0,1,0] op_sel_hi:[1,1,1]
	v_pk_fma_f32 v[4:5], v[90:91], v[52:53], v[4:5] op_sel:[0,1,0] op_sel_hi:[1,1,1]
	v_pk_fma_f32 v[6:7], v[90:91], v[50:51], v[6:7] op_sel:[0,1,0] op_sel_hi:[1,1,1]
	v_pk_fma_f32 v[8:9], v[90:91], v[48:49], v[8:9] op_sel:[0,1,0] op_sel_hi:[1,1,1]
	v_pk_fma_f32 v[10:11], v[90:91], v[46:47], v[10:11] op_sel:[0,1,0] op_sel_hi:[1,1,1]
	v_pk_fma_f32 v[12:13], v[90:91], v[44:45], v[12:13] op_sel:[0,1,0] op_sel_hi:[1,1,1]
	v_pk_fma_f32 v[14:15], v[90:91], v[42:43], v[14:15] op_sel:[0,1,0] op_sel_hi:[1,1,1]
	v_pk_fma_f32 v[16:17], v[90:91], v[40:41], v[16:17] op_sel:[0,1,0] op_sel_hi:[1,1,1]
	v_pk_fma_f32 v[18:19], v[90:91], v[38:39], v[18:19] op_sel:[0,1,0] op_sel_hi:[1,1,1]
	v_pk_fma_f32 v[20:21], v[90:91], v[36:37], v[20:21] op_sel:[0,1,0] op_sel_hi:[1,1,1]
	v_pk_fma_f32 v[22:23], v[90:91], v[34:35], v[22:23] op_sel:[0,1,0] op_sel_hi:[1,1,1]
	v_pk_fma_f32 v[24:25], v[90:91], v[32:33], v[24:25] op_sel:[0,1,0] op_sel_hi:[1,1,1]
	ds_read2st64_b32 v[74:75], v96 offset0:128 offset1:132
	s_waitcnt lgkmcnt(6)
	v_pk_fma_f32 v[0:1], v[92:93], v[58:59], v[0:1] op_sel_hi:[1,0,1]
	v_pk_fma_f32 v[2:3], v[92:93], v[56:57], v[2:3] op_sel_hi:[1,0,1]
	v_pk_fma_f32 v[4:5], v[92:93], v[54:55], v[4:5] op_sel_hi:[1,0,1]
	v_pk_fma_f32 v[6:7], v[92:93], v[52:53], v[6:7] op_sel_hi:[1,0,1]
	v_pk_fma_f32 v[8:9], v[92:93], v[50:51], v[8:9] op_sel_hi:[1,0,1]
	v_pk_fma_f32 v[10:11], v[92:93], v[48:49], v[10:11] op_sel_hi:[1,0,1]
	v_pk_fma_f32 v[12:13], v[92:93], v[46:47], v[12:13] op_sel_hi:[1,0,1]
	v_pk_fma_f32 v[14:15], v[92:93], v[44:45], v[14:15] op_sel_hi:[1,0,1]
	v_pk_fma_f32 v[16:17], v[92:93], v[42:43], v[16:17] op_sel_hi:[1,0,1]
	v_pk_fma_f32 v[18:19], v[92:93], v[40:41], v[18:19] op_sel_hi:[1,0,1]
	v_pk_fma_f32 v[20:21], v[92:93], v[38:39], v[20:21] op_sel_hi:[1,0,1]
	v_pk_fma_f32 v[22:23], v[92:93], v[36:37], v[22:23] op_sel_hi:[1,0,1]
	v_pk_fma_f32 v[24:25], v[92:93], v[34:35], v[24:25] op_sel_hi:[1,0,1]
	v_pk_fma_f32 v[26:27], v[92:93], v[32:33], v[64:65] op_sel_hi:[1,0,0]
	ds_read2st64_b32 v[76:77], v96 offset0:132 offset1:136
	s_waitcnt lgkmcnt(6)
	v_pk_fma_f32 v[0:1], v[94:95], v[58:59], v[0:1] op_sel:[0,1,0] op_sel_hi:[1,1,1]
	v_pk_fma_f32 v[2:3], v[94:95], v[56:57], v[2:3] op_sel:[0,1,0] op_sel_hi:[1,1,1]
	v_pk_fma_f32 v[4:5], v[94:95], v[54:55], v[4:5] op_sel:[0,1,0] op_sel_hi:[1,1,1]
	v_pk_fma_f32 v[6:7], v[94:95], v[52:53], v[6:7] op_sel:[0,1,0] op_sel_hi:[1,1,1]
	v_pk_fma_f32 v[8:9], v[94:95], v[50:51], v[8:9] op_sel:[0,1,0] op_sel_hi:[1,1,1]
	v_pk_fma_f32 v[10:11], v[94:95], v[48:49], v[10:11] op_sel:[0,1,0] op_sel_hi:[1,1,1]
	v_pk_fma_f32 v[12:13], v[94:95], v[46:47], v[12:13] op_sel:[0,1,0] op_sel_hi:[1,1,1]
	v_pk_fma_f32 v[14:15], v[94:95], v[44:45], v[14:15] op_sel:[0,1,0] op_sel_hi:[1,1,1]
	v_pk_fma_f32 v[16:17], v[94:95], v[42:43], v[16:17] op_sel:[0,1,0] op_sel_hi:[1,1,1]
	v_pk_fma_f32 v[18:19], v[94:95], v[40:41], v[18:19] op_sel:[0,1,0] op_sel_hi:[1,1,1]
	v_pk_fma_f32 v[20:21], v[94:95], v[38:39], v[20:21] op_sel:[0,1,0] op_sel_hi:[1,1,1]
	v_pk_fma_f32 v[22:23], v[94:95], v[36:37], v[22:23] op_sel:[0,1,0] op_sel_hi:[1,1,1]
	v_pk_fma_f32 v[24:25], v[94:95], v[34:35], v[24:25] op_sel:[0,1,0] op_sel_hi:[1,1,1]
	v_pk_fma_f32 v[26:27], v[94:95], v[32:33], v[26:27] op_sel:[0,1,0] op_sel_hi:[1,1,1]
	ds_read2st64_b32 v[78:79], v96 offset0:136 offset1:140
	s_waitcnt lgkmcnt(6)
	v_pk_fma_f32 v[0:1], v[66:67], v[60:61], v[0:1] op_sel_hi:[1,0,1]
	v_pk_fma_f32 v[2:3], v[66:67], v[58:59], v[2:3] op_sel_hi:[1,0,1]
	v_pk_fma_f32 v[4:5], v[66:67], v[56:57], v[4:5] op_sel_hi:[1,0,1]
	v_pk_fma_f32 v[6:7], v[66:67], v[54:55], v[6:7] op_sel_hi:[1,0,1]
	v_pk_fma_f32 v[8:9], v[66:67], v[52:53], v[8:9] op_sel_hi:[1,0,1]
	v_pk_fma_f32 v[10:11], v[66:67], v[50:51], v[10:11] op_sel_hi:[1,0,1]
	v_pk_fma_f32 v[12:13], v[66:67], v[48:49], v[12:13] op_sel_hi:[1,0,1]
	v_pk_fma_f32 v[14:15], v[66:67], v[46:47], v[14:15] op_sel_hi:[1,0,1]
	v_pk_fma_f32 v[16:17], v[66:67], v[44:45], v[16:17] op_sel_hi:[1,0,1]
	v_pk_fma_f32 v[18:19], v[66:67], v[42:43], v[18:19] op_sel_hi:[1,0,1]
	v_pk_fma_f32 v[20:21], v[66:67], v[40:41], v[20:21] op_sel_hi:[1,0,1]
	v_pk_fma_f32 v[22:23], v[66:67], v[38:39], v[22:23] op_sel_hi:[1,0,1]
	v_pk_fma_f32 v[24:25], v[66:67], v[36:37], v[24:25] op_sel_hi:[1,0,1]
	v_pk_fma_f32 v[26:27], v[66:67], v[34:35], v[26:27] op_sel_hi:[1,0,1]
	v_pk_fma_f32 v[28:29], v[66:67], v[32:33], v[64:65] op_sel_hi:[1,0,0]
	ds_read2st64_b32 v[82:83], v96 offset0:140 offset1:144
	s_waitcnt lgkmcnt(6)
	v_pk_fma_f32 v[0:1], v[68:69], v[60:61], v[0:1] op_sel:[0,1,0] op_sel_hi:[1,1,1]
	v_pk_fma_f32 v[2:3], v[68:69], v[58:59], v[2:3] op_sel:[0,1,0] op_sel_hi:[1,1,1]
	v_pk_fma_f32 v[4:5], v[68:69], v[56:57], v[4:5] op_sel:[0,1,0] op_sel_hi:[1,1,1]
	v_pk_fma_f32 v[6:7], v[68:69], v[54:55], v[6:7] op_sel:[0,1,0] op_sel_hi:[1,1,1]
	v_pk_fma_f32 v[8:9], v[68:69], v[52:53], v[8:9] op_sel:[0,1,0] op_sel_hi:[1,1,1]
	v_pk_fma_f32 v[10:11], v[68:69], v[50:51], v[10:11] op_sel:[0,1,0] op_sel_hi:[1,1,1]
	v_pk_fma_f32 v[12:13], v[68:69], v[48:49], v[12:13] op_sel:[0,1,0] op_sel_hi:[1,1,1]
	v_pk_fma_f32 v[14:15], v[68:69], v[46:47], v[14:15] op_sel:[0,1,0] op_sel_hi:[1,1,1]
	v_pk_fma_f32 v[16:17], v[68:69], v[44:45], v[16:17] op_sel:[0,1,0] op_sel_hi:[1,1,1]
	v_pk_fma_f32 v[18:19], v[68:69], v[42:43], v[18:19] op_sel:[0,1,0] op_sel_hi:[1,1,1]
	v_pk_fma_f32 v[20:21], v[68:69], v[40:41], v[20:21] op_sel:[0,1,0] op_sel_hi:[1,1,1]
	v_pk_fma_f32 v[22:23], v[68:69], v[38:39], v[22:23] op_sel:[0,1,0] op_sel_hi:[1,1,1]
	v_pk_fma_f32 v[24:25], v[68:69], v[36:37], v[24:25] op_sel:[0,1,0] op_sel_hi:[1,1,1]
	v_pk_fma_f32 v[26:27], v[68:69], v[34:35], v[26:27] op_sel:[0,1,0] op_sel_hi:[1,1,1]
	v_pk_fma_f32 v[28:29], v[68:69], v[32:33], v[28:29] op_sel:[0,1,0] op_sel_hi:[1,1,1]
	ds_read2st64_b32 v[84:85], v96 offset0:144 offset1:148
	s_waitcnt lgkmcnt(6)
; __device__ __forceinline__ void conv_unit(Ctx& F, const bf16* P, bf16* O, int seq_row0, int seq_len, int t0, const float* wdw, const float* bdw, const float* lng, const float* lnb) {
;     ...
;     for (int tt = 0; tt < 32; ++tt) { float a = bb; const float* yp = y + (hf * 32 + tt) * 256 + c;
; #pragma unroll
;         for (int k = 0; k < 31; ++k) a += w[k] * yp[k * 256];
;         outv[tt] = a; }
	v_pk_fma_f32 v[0:1], v[70:71], v[62:63], v[0:1] op_sel_hi:[1,0,1]
	v_pk_fma_f32 v[2:3], v[70:71], v[60:61], v[2:3] op_sel_hi:[1,0,1]
	v_pk_fma_f32 v[4:5], v[70:71], v[58:59], v[4:5] op_sel_hi:[1,0,1]
	v_pk_fma_f32 v[6:7], v[70:71], v[56:57], v[6:7] op_sel_hi:[1,0,1]
	v_pk_fma_f32 v[8:9], v[70:71], v[54:55], v[8:9] op_sel_hi:[1,0,1]
	v_pk_fma_f32 v[10:11], v[70:71], v[52:53], v[10:11] op_sel_hi:[1,0,1]
	v_pk_fma_f32 v[12:13], v[70:71], v[50:51], v[12:13] op_sel_hi:[1,0,1]
	v_pk_fma_f32 v[14:15], v[70:71], v[48:49], v[14:15] op_sel_hi:[1,0,1]
	v_pk_fma_f32 v[16:17], v[70:71], v[46:47], v[16:17] op_sel_hi:[1,0,1]
	v_pk_fma_f32 v[18:19], v[70:71], v[44:45], v[18:19] op_sel_hi:[1,0,1]
	v_pk_fma_f32 v[20:21], v[70:71], v[42:43], v[20:21] op_sel_hi:[1,0,1]
	v_pk_fma_f32 v[22:23], v[70:71], v[40:41], v[22:23] op_sel_hi:[1,0,1]
	v_pk_fma_f32 v[24:25], v[70:71], v[38:39], v[24:25] op_sel_hi:[1,0,1]
	v_pk_fma_f32 v[26:27], v[70:71], v[36:37], v[26:27] op_sel_hi:[1,0,1]
	v_pk_fma_f32 v[28:29], v[70:71], v[34:35], v[28:29] op_sel_hi:[1,0,1]
	v_pk_fma_f32 v[30:31], v[70:71], v[32:33], v[64:65] op_sel_hi:[1,0,0]
	ds_read2st64_b32 v[86:87], v96 offset0:148 offset1:152
	s_waitcnt lgkmcnt(6)
	v_pk_fma_f32 v[2:3], v[72:73], v[60:61], v[2:3] op_sel:[0,1,0] op_sel_hi:[1,1,1]
	v_pk_fma_f32 v[4:5], v[72:73], v[58:59], v[4:5] op_sel:[0,1,0] op_sel_hi:[1,1,1]
	v_pk_fma_f32 v[6:7], v[72:73], v[56:57], v[6:7] op_sel:[0,1,0] op_sel_hi:[1,1,1]
	v_pk_fma_f32 v[8:9], v[72:73], v[54:55], v[8:9] op_sel:[0,1,0] op_sel_hi:[1,1,1]
	v_pk_fma_f32 v[10:11], v[72:73], v[52:53], v[10:11] op_sel:[0,1,0] op_sel_hi:[1,1,1]
	v_pk_fma_f32 v[12:13], v[72:73], v[50:51], v[12:13] op_sel:[0,1,0] op_sel_hi:[1,1,1]
	v_pk_fma_f32 v[14:15], v[72:73], v[48:49], v[14:15] op_sel:[0,1,0] op_sel_hi:[1,1,1]
	v_pk_fma_f32 v[16:17], v[72:73], v[46:47], v[16:17] op_sel:[0,1,0] op_sel_hi:[1,1,1]
	v_pk_fma_f32 v[18:19], v[72:73], v[44:45], v[18:19] op_sel:[0,1,0] op_sel_hi:[1,1,1]
	v_pk_fma_f32 v[20:21], v[72:73], v[42:43], v[20:21] op_sel:[0,1,0] op_sel_hi:[1,1,1]
	v_pk_fma_f32 v[22:23], v[72:73], v[40:41], v[22:23] op_sel:[0,1,0] op_sel_hi:[1,1,1]
	v_pk_fma_f32 v[24:25], v[72:73], v[38:39], v[24:25] op_sel:[0,1,0] op_sel_hi:[1,1,1]
	v_pk_fma_f32 v[26:27], v[72:73], v[36:37], v[26:27] op_sel:[0,1,0] op_sel_hi:[1,1,1]
	v_pk_fma_f32 v[28:29], v[72:73], v[34:35], v[28:29] op_sel:[0,1,0] op_sel_hi:[1,1,1]
	v_pk_fma_f32 v[30:31], v[72:73], v[32:33], v[30:31] op_sel:[0,1,0] op_sel_hi:[1,1,1]
	ds_read2st64_b32 v[88:89], v96 offset0:152 offset1:156
	s_waitcnt lgkmcnt(6)
	v_pk_fma_f32 v[2:3], v[74:75], v[62:63], v[2:3] op_sel_hi:[1,0,1]
	v_pk_fma_f32 v[4:5], v[74:75], v[60:61], v[4:5] op_sel_hi:[1,0,1]
	v_pk_fma_f32 v[6:7], v[74:75], v[58:59], v[6:7] op_sel_hi:[1,0,1]
	v_pk_fma_f32 v[8:9], v[74:75], v[56:57], v[8:9] op_sel_hi:[1,0,1]
	v_pk_fma_f32 v[10:11], v[74:75], v[54:55], v[10:11] op_sel_hi:[1,0,1]
	v_pk_fma_f32 v[12:13], v[74:75], v[52:53], v[12:13] op_sel_hi:[1,0,1]
	v_pk_fma_f32 v[14:15], v[74:75], v[50:51], v[14:15] op_sel_hi:[1,0,1]
	v_pk_fma_f32 v[16:17], v[74:75], v[48:49], v[16:17] op_sel_hi:[1,0,1]
	v_pk_fma_f32 v[18:19], v[74:75], v[46:47], v[18:19] op_sel_hi:[1,0,1]
	v_pk_fma_f32 v[20:21], v[74:75], v[44:45], v[20:21] op_sel_hi:[1,0,1]
	v_pk_fma_f32 v[22:23], v[74:75], v[42:43], v[22:23] op_sel_hi:[1,0,1]
	v_pk_fma_f32 v[24:25], v[74:75], v[40:41], v[24:25] op_sel_hi:[1,0,1]
	v_pk_fma_f32 v[26:27], v[74:75], v[38:39], v[26:27] op_sel_hi:[1,0,1]
	v_pk_fma_f32 v[28:29], v[74:75], v[36:37], v[28:29] op_sel_hi:[1,0,1]
	v_pk_fma_f32 v[30:31], v[74:75], v[34:35], v[30:31] op_sel_hi:[1,0,1]
	ds_read2st64_b32 v[90:91], v96 offset0:156 offset1:160
	s_waitcnt lgkmcnt(6)
	v_pk_fma_f32 v[4:5], v[76:77], v[60:61], v[4:5] op_sel:[0,1,0] op_sel_hi:[1,1,1]
	v_pk_fma_f32 v[6:7], v[76:77], v[58:59], v[6:7] op_sel:[0,1,0] op_sel_hi:[1,1,1]
	v_pk_fma_f32 v[8:9], v[76:77], v[56:57], v[8:9] op_sel:[0,1,0] op_sel_hi:[1,1,1]
	v_pk_fma_f32 v[10:11], v[76:77], v[54:55], v[10:11] op_sel:[0,1,0] op_sel_hi:[1,1,1]
	v_pk_fma_f32 v[12:13], v[76:77], v[52:53], v[12:13] op_sel:[0,1,0] op_sel_hi:[1,1,1]
	v_pk_fma_f32 v[14:15], v[76:77], v[50:51], v[14:15] op_sel:[0,1,0] op_sel_hi:[1,1,1]
	v_pk_fma_f32 v[16:17], v[76:77], v[48:49], v[16:17] op_sel:[0,1,0] op_sel_hi:[1,1,1]
	v_pk_fma_f32 v[18:19], v[76:77], v[46:47], v[18:19] op_sel:[0,1,0] op_sel_hi:[1,1,1]
	v_pk_fma_f32 v[20:21], v[76:77], v[44:45], v[20:21] op_sel:[0,1,0] op_sel_hi:[1,1,1]
	v_pk_fma_f32 v[22:23], v[76:77], v[42:43], v[22:23] op_sel:[0,1,0] op_sel_hi:[1,1,1]
	v_pk_fma_f32 v[24:25], v[76:77], v[40:41], v[24:25] op_sel:[0,1,0] op_sel_hi:[1,1,1]
	v_pk_fma_f32 v[26:27], v[76:77], v[38:39], v[26:27] op_sel:[0,1,0] op_sel_hi:[1,1,1]
	v_pk_fma_f32 v[28:29], v[76:77], v[36:37], v[28:29] op_sel:[0,1,0] op_sel_hi:[1,1,1]
	v_pk_fma_f32 v[30:31], v[76:77], v[34:35], v[30:31] op_sel:[0,1,0] op_sel_hi:[1,1,1]
	ds_read2st64_b32 v[92:93], v96 offset0:160 offset1:164
	s_waitcnt lgkmcnt(6)
	v_pk_fma_f32 v[4:5], v[78:79], v[62:63], v[4:5] op_sel_hi:[1,0,1]
	v_pk_fma_f32 v[6:7], v[78:79], v[60:61], v[6:7] op_sel_hi:[1,0,1]
	v_pk_fma_f32 v[8:9], v[78:79], v[58:59], v[8:9] op_sel_hi:[1,0,1]
	v_pk_fma_f32 v[10:11], v[78:79], v[56:57], v[10:11] op_sel_hi:[1,0,1]
	v_pk_fma_f32 v[12:13], v[78:79], v[54:55], v[12:13] op_sel_hi:[1,0,1]
	v_pk_fma_f32 v[14:15], v[78:79], v[52:53], v[14:15] op_sel_hi:[1,0,1]
	v_pk_fma_f32 v[16:17], v[78:79], v[50:51], v[16:17] op_sel_hi:[1,0,1]
	v_pk_fma_f32 v[18:19], v[78:79], v[48:49], v[18:19] op_sel_hi:[1,0,1]
	v_pk_fma_f32 v[20:21], v[78:79], v[46:47], v[20:21] op_sel_hi:[1,0,1]
	v_pk_fma_f32 v[22:23], v[78:79], v[44:45], v[22:23] op_sel_hi:[1,0,1]
	v_pk_fma_f32 v[24:25], v[78:79], v[42:43], v[24:25] op_sel_hi:[1,0,1]
	v_pk_fma_f32 v[26:27], v[78:79], v[40:41], v[26:27] op_sel_hi:[1,0,1]
	v_pk_fma_f32 v[28:29], v[78:79], v[38:39], v[28:29] op_sel_hi:[1,0,1]
	v_pk_fma_f32 v[30:31], v[78:79], v[36:37], v[30:31] op_sel_hi:[1,0,1]
	ds_read2st64_b32 v[94:95], v96 offset0:164 offset1:168
	s_waitcnt lgkmcnt(6)
; __device__ __forceinline__ void conv_unit(Ctx& F, const bf16* P, bf16* O, int seq_row0, int seq_len, int t0, const float* wdw, const float* bdw, const float* lng, const float* lnb) {
;     ...
;     for (int tt = 0; tt < 32; ++tt) { float a = bb; const float* yp = y + (hf * 32 + tt) * 256 + c;
; #pragma unroll
;         for (int k = 0; k < 31; ++k) a += w[k] * yp[k * 256];
;         outv[tt] = a; }
	v_pk_fma_f32 v[6:7], v[82:83], v[60:61], v[6:7] op_sel:[0,1,0] op_sel_hi:[1,1,1]
	v_pk_fma_f32 v[8:9], v[82:83], v[58:59], v[8:9] op_sel:[0,1,0] op_sel_hi:[1,1,1]
	v_pk_fma_f32 v[10:11], v[82:83], v[56:57], v[10:11] op_sel:[0,1,0] op_sel_hi:[1,1,1]
	v_pk_fma_f32 v[12:13], v[82:83], v[54:55], v[12:13] op_sel:[0,1,0] op_sel_hi:[1,1,1]
	v_pk_fma_f32 v[14:15], v[82:83], v[52:53], v[14:15] op_sel:[0,1,0] op_sel_hi:[1,1,1]
	v_pk_fma_f32 v[16:17], v[82:83], v[50:51], v[16:17] op_sel:[0,1,0] op_sel_hi:[1,1,1]
	v_pk_fma_f32 v[18:19], v[82:83], v[48:49], v[18:19] op_sel:[0,1,0] op_sel_hi:[1,1,1]
	v_pk_fma_f32 v[20:21], v[82:83], v[46:47], v[20:21] op_sel:[0,1,0] op_sel_hi:[1,1,1]
	v_pk_fma_f32 v[22:23], v[82:83], v[44:45], v[22:23] op_sel:[0,1,0] op_sel_hi:[1,1,1]
	v_pk_fma_f32 v[24:25], v[82:83], v[42:43], v[24:25] op_sel:[0,1,0] op_sel_hi:[1,1,1]
	v_pk_fma_f32 v[26:27], v[82:83], v[40:41], v[26:27] op_sel:[0,1,0] op_sel_hi:[1,1,1]
	v_pk_fma_f32 v[28:29], v[82:83], v[38:39], v[28:29] op_sel:[0,1,0] op_sel_hi:[1,1,1]
	v_pk_fma_f32 v[30:31], v[82:83], v[36:37], v[30:31] op_sel:[0,1,0] op_sel_hi:[1,1,1]
	ds_read2st64_b32 v[66:67], v96 offset0:168 offset1:172
	s_waitcnt lgkmcnt(6)
	v_pk_fma_f32 v[6:7], v[84:85], v[62:63], v[6:7] op_sel_hi:[1,0,1]
	v_pk_fma_f32 v[8:9], v[84:85], v[60:61], v[8:9] op_sel_hi:[1,0,1]
	v_pk_fma_f32 v[10:11], v[84:85], v[58:59], v[10:11] op_sel_hi:[1,0,1]
	v_pk_fma_f32 v[12:13], v[84:85], v[56:57], v[12:13] op_sel_hi:[1,0,1]
	v_pk_fma_f32 v[14:15], v[84:85], v[54:55], v[14:15] op_sel_hi:[1,0,1]
	v_pk_fma_f32 v[16:17], v[84:85], v[52:53], v[16:17] op_sel_hi:[1,0,1]
	v_pk_fma_f32 v[18:19], v[84:85], v[50:51], v[18:19] op_sel_hi:[1,0,1]
	v_pk_fma_f32 v[20:21], v[84:85], v[48:49], v[20:21] op_sel_hi:[1,0,1]
	v_pk_fma_f32 v[22:23], v[84:85], v[46:47], v[22:23] op_sel_hi:[1,0,1]
	v_pk_fma_f32 v[24:25], v[84:85], v[44:45], v[24:25] op_sel_hi:[1,0,1]
	v_pk_fma_f32 v[26:27], v[84:85], v[42:43], v[26:27] op_sel_hi:[1,0,1]
	v_pk_fma_f32 v[28:29], v[84:85], v[40:41], v[28:29] op_sel_hi:[1,0,1]
	v_pk_fma_f32 v[30:31], v[84:85], v[38:39], v[30:31] op_sel_hi:[1,0,1]
	ds_read2st64_b32 v[68:69], v96 offset0:172 offset1:176
	s_waitcnt lgkmcnt(6)
	v_pk_fma_f32 v[8:9], v[86:87], v[60:61], v[8:9] op_sel:[0,1,0] op_sel_hi:[1,1,1]
	v_pk_fma_f32 v[10:11], v[86:87], v[58:59], v[10:11] op_sel:[0,1,0] op_sel_hi:[1,1,1]
	v_pk_fma_f32 v[12:13], v[86:87], v[56:57], v[12:13] op_sel:[0,1,0] op_sel_hi:[1,1,1]
	v_pk_fma_f32 v[14:15], v[86:87], v[54:55], v[14:15] op_sel:[0,1,0] op_sel_hi:[1,1,1]
	v_pk_fma_f32 v[16:17], v[86:87], v[52:53], v[16:17] op_sel:[0,1,0] op_sel_hi:[1,1,1]
	v_pk_fma_f32 v[18:19], v[86:87], v[50:51], v[18:19] op_sel:[0,1,0] op_sel_hi:[1,1,1]
	v_pk_fma_f32 v[20:21], v[86:87], v[48:49], v[20:21] op_sel:[0,1,0] op_sel_hi:[1,1,1]
	v_pk_fma_f32 v[22:23], v[86:87], v[46:47], v[22:23] op_sel:[0,1,0] op_sel_hi:[1,1,1]
	v_pk_fma_f32 v[24:25], v[86:87], v[44:45], v[24:25] op_sel:[0,1,0] op_sel_hi:[1,1,1]
	v_pk_fma_f32 v[26:27], v[86:87], v[42:43], v[26:27] op_sel:[0,1,0] op_sel_hi:[1,1,1]
	v_pk_fma_f32 v[28:29], v[86:87], v[40:41], v[28:29] op_sel:[0,1,0] op_sel_hi:[1,1,1]
	v_pk_fma_f32 v[30:31], v[86:87], v[38:39], v[30:31] op_sel:[0,1,0] op_sel_hi:[1,1,1]
	ds_read2st64_b32 v[70:71], v96 offset0:176 offset1:180
	s_waitcnt lgkmcnt(6)
	v_pk_fma_f32 v[8:9], v[88:89], v[62:63], v[8:9] op_sel_hi:[1,0,1]
	v_pk_fma_f32 v[10:11], v[88:89], v[60:61], v[10:11] op_sel_hi:[1,0,1]
	v_pk_fma_f32 v[12:13], v[88:89], v[58:59], v[12:13] op_sel_hi:[1,0,1]
	v_pk_fma_f32 v[14:15], v[88:89], v[56:57], v[14:15] op_sel_hi:[1,0,1]
	v_pk_fma_f32 v[16:17], v[88:89], v[54:55], v[16:17] op_sel_hi:[1,0,1]
	v_pk_fma_f32 v[18:19], v[88:89], v[52:53], v[18:19] op_sel_hi:[1,0,1]
	v_pk_fma_f32 v[20:21], v[88:89], v[50:51], v[20:21] op_sel_hi:[1,0,1]
	v_pk_fma_f32 v[22:23], v[88:89], v[48:49], v[22:23] op_sel_hi:[1,0,1]
	v_pk_fma_f32 v[24:25], v[88:89], v[46:47], v[24:25] op_sel_hi:[1,0,1]
	v_pk_fma_f32 v[26:27], v[88:89], v[44:45], v[26:27] op_sel_hi:[1,0,1]
	v_pk_fma_f32 v[28:29], v[88:89], v[42:43], v[28:29] op_sel_hi:[1,0,1]
	v_pk_fma_f32 v[30:31], v[88:89], v[40:41], v[30:31] op_sel_hi:[1,0,1]
	ds_read2st64_b32 v[72:73], v96 offset0:180 offset1:184
	s_waitcnt lgkmcnt(6)
	v_pk_fma_f32 v[10:11], v[90:91], v[60:61], v[10:11] op_sel:[0,1,0] op_sel_hi:[1,1,1]
	v_pk_fma_f32 v[12:13], v[90:91], v[58:59], v[12:13] op_sel:[0,1,0] op_sel_hi:[1,1,1]
	v_pk_fma_f32 v[14:15], v[90:91], v[56:57], v[14:15] op_sel:[0,1,0] op_sel_hi:[1,1,1]
	v_pk_fma_f32 v[16:17], v[90:91], v[54:55], v[16:17] op_sel:[0,1,0] op_sel_hi:[1,1,1]
	v_pk_fma_f32 v[18:19], v[90:91], v[52:53], v[18:19] op_sel:[0,1,0] op_sel_hi:[1,1,1]
	v_pk_fma_f32 v[20:21], v[90:91], v[50:51], v[20:21] op_sel:[0,1,0] op_sel_hi:[1,1,1]
	v_pk_fma_f32 v[22:23], v[90:91], v[48:49], v[22:23] op_sel:[0,1,0] op_sel_hi:[1,1,1]
	v_pk_fma_f32 v[24:25], v[90:91], v[46:47], v[24:25] op_sel:[0,1,0] op_sel_hi:[1,1,1]
	v_pk_fma_f32 v[26:27], v[90:91], v[44:45], v[26:27] op_sel:[0,1,0] op_sel_hi:[1,1,1]
	v_pk_fma_f32 v[28:29], v[90:91], v[42:43], v[28:29] op_sel:[0,1,0] op_sel_hi:[1,1,1]
	v_pk_fma_f32 v[30:31], v[90:91], v[40:41], v[30:31] op_sel:[0,1,0] op_sel_hi:[1,1,1]
	ds_read2st64_b32 v[74:75], v96 offset0:184 offset1:188
	s_waitcnt lgkmcnt(6)
; __device__ __forceinline__ void conv_unit(Ctx& F, const bf16* P, bf16* O, int seq_row0, int seq_len, int t0, const float* wdw, const float* bdw, const float* lng, const float* lnb) {
;     ...
;     for (int tt = 0; tt < 32; ++tt) { float a = bb; const float* yp = y + (hf * 32 + tt) * 256 + c;
; #pragma unroll
;         for (int k = 0; k < 31; ++k) a += w[k] * yp[k * 256];
;         outv[tt] = a; }
	v_pk_fma_f32 v[10:11], v[92:93], v[62:63], v[10:11] op_sel_hi:[1,0,1]
	v_pk_fma_f32 v[12:13], v[92:93], v[60:61], v[12:13] op_sel_hi:[1,0,1]
	v_pk_fma_f32 v[14:15], v[92:93], v[58:59], v[14:15] op_sel_hi:[1,0,1]
	v_pk_fma_f32 v[16:17], v[92:93], v[56:57], v[16:17] op_sel_hi:[1,0,1]
	v_pk_fma_f32 v[18:19], v[92:93], v[54:55], v[18:19] op_sel_hi:[1,0,1]
	v_pk_fma_f32 v[20:21], v[92:93], v[52:53], v[20:21] op_sel_hi:[1,0,1]
	v_pk_fma_f32 v[22:23], v[92:93], v[50:51], v[22:23] op_sel_hi:[1,0,1]
	v_pk_fma_f32 v[24:25], v[92:93], v[48:49], v[24:25] op_sel_hi:[1,0,1]
	v_pk_fma_f32 v[26:27], v[92:93], v[46:47], v[26:27] op_sel_hi:[1,0,1]
	v_pk_fma_f32 v[28:29], v[92:93], v[44:45], v[28:29] op_sel_hi:[1,0,1]
	v_pk_fma_f32 v[30:31], v[92:93], v[42:43], v[30:31] op_sel_hi:[1,0,1]
	ds_read2st64_b32 v[76:77], v96 offset0:188 offset1:192
	s_waitcnt lgkmcnt(6)
	v_pk_fma_f32 v[12:13], v[94:95], v[60:61], v[12:13] op_sel:[0,1,0] op_sel_hi:[1,1,1]
	v_pk_fma_f32 v[14:15], v[94:95], v[58:59], v[14:15] op_sel:[0,1,0] op_sel_hi:[1,1,1]
	v_pk_fma_f32 v[16:17], v[94:95], v[56:57], v[16:17] op_sel:[0,1,0] op_sel_hi:[1,1,1]
	v_pk_fma_f32 v[18:19], v[94:95], v[54:55], v[18:19] op_sel:[0,1,0] op_sel_hi:[1,1,1]
	v_pk_fma_f32 v[20:21], v[94:95], v[52:53], v[20:21] op_sel:[0,1,0] op_sel_hi:[1,1,1]
	v_pk_fma_f32 v[22:23], v[94:95], v[50:51], v[22:23] op_sel:[0,1,0] op_sel_hi:[1,1,1]
	v_pk_fma_f32 v[24:25], v[94:95], v[48:49], v[24:25] op_sel:[0,1,0] op_sel_hi:[1,1,1]
	v_pk_fma_f32 v[26:27], v[94:95], v[46:47], v[26:27] op_sel:[0,1,0] op_sel_hi:[1,1,1]
	v_pk_fma_f32 v[28:29], v[94:95], v[44:45], v[28:29] op_sel:[0,1,0] op_sel_hi:[1,1,1]
	v_pk_fma_f32 v[30:31], v[94:95], v[42:43], v[30:31] op_sel:[0,1,0] op_sel_hi:[1,1,1]
	ds_read2st64_b32 v[78:79], v96 offset0:192 offset1:196
	s_waitcnt lgkmcnt(6)
	v_pk_fma_f32 v[12:13], v[66:67], v[62:63], v[12:13] op_sel_hi:[1,0,1]
	v_pk_fma_f32 v[14:15], v[66:67], v[60:61], v[14:15] op_sel_hi:[1,0,1]
	v_pk_fma_f32 v[16:17], v[66:67], v[58:59], v[16:17] op_sel_hi:[1,0,1]
	v_pk_fma_f32 v[18:19], v[66:67], v[56:57], v[18:19] op_sel_hi:[1,0,1]
	v_pk_fma_f32 v[20:21], v[66:67], v[54:55], v[20:21] op_sel_hi:[1,0,1]
	v_pk_fma_f32 v[22:23], v[66:67], v[52:53], v[22:23] op_sel_hi:[1,0,1]
	v_pk_fma_f32 v[24:25], v[66:67], v[50:51], v[24:25] op_sel_hi:[1,0,1]
	v_pk_fma_f32 v[26:27], v[66:67], v[48:49], v[26:27] op_sel_hi:[1,0,1]
	v_pk_fma_f32 v[28:29], v[66:67], v[46:47], v[28:29] op_sel_hi:[1,0,1]
	v_pk_fma_f32 v[30:31], v[66:67], v[44:45], v[30:31] op_sel_hi:[1,0,1]
	ds_read2st64_b32 v[82:83], v96 offset0:196 offset1:200
	s_waitcnt lgkmcnt(6)
	v_pk_fma_f32 v[14:15], v[68:69], v[60:61], v[14:15] op_sel:[0,1,0] op_sel_hi:[1,1,1]
	v_pk_fma_f32 v[16:17], v[68:69], v[58:59], v[16:17] op_sel:[0,1,0] op_sel_hi:[1,1,1]
	v_pk_fma_f32 v[18:19], v[68:69], v[56:57], v[18:19] op_sel:[0,1,0] op_sel_hi:[1,1,1]
	v_pk_fma_f32 v[20:21], v[68:69], v[54:55], v[20:21] op_sel:[0,1,0] op_sel_hi:[1,1,1]
	v_pk_fma_f32 v[22:23], v[68:69], v[52:53], v[22:23] op_sel:[0,1,0] op_sel_hi:[1,1,1]
	v_pk_fma_f32 v[24:25], v[68:69], v[50:51], v[24:25] op_sel:[0,1,0] op_sel_hi:[1,1,1]
	v_pk_fma_f32 v[26:27], v[68:69], v[48:49], v[26:27] op_sel:[0,1,0] op_sel_hi:[1,1,1]
	v_pk_fma_f32 v[28:29], v[68:69], v[46:47], v[28:29] op_sel:[0,1,0] op_sel_hi:[1,1,1]
	v_pk_fma_f32 v[30:31], v[68:69], v[44:45], v[30:31] op_sel:[0,1,0] op_sel_hi:[1,1,1]
	ds_read2st64_b32 v[84:85], v96 offset0:200 offset1:204
	s_waitcnt lgkmcnt(6)
	v_pk_fma_f32 v[14:15], v[70:71], v[62:63], v[14:15] op_sel_hi:[1,0,1]
	v_pk_fma_f32 v[16:17], v[70:71], v[60:61], v[16:17] op_sel_hi:[1,0,1]
	v_pk_fma_f32 v[18:19], v[70:71], v[58:59], v[18:19] op_sel_hi:[1,0,1]
	v_pk_fma_f32 v[20:21], v[70:71], v[56:57], v[20:21] op_sel_hi:[1,0,1]
	v_pk_fma_f32 v[22:23], v[70:71], v[54:55], v[22:23] op_sel_hi:[1,0,1]
	v_pk_fma_f32 v[24:25], v[70:71], v[52:53], v[24:25] op_sel_hi:[1,0,1]
	v_pk_fma_f32 v[26:27], v[70:71], v[50:51], v[26:27] op_sel_hi:[1,0,1]
	v_pk_fma_f32 v[28:29], v[70:71], v[48:49], v[28:29] op_sel_hi:[1,0,1]
	v_pk_fma_f32 v[30:31], v[70:71], v[46:47], v[30:31] op_sel_hi:[1,0,1]
	ds_read2st64_b32 v[86:87], v96 offset0:204 offset1:208
	s_waitcnt lgkmcnt(6)
	v_pk_fma_f32 v[16:17], v[72:73], v[60:61], v[16:17] op_sel:[0,1,0] op_sel_hi:[1,1,1]
	v_pk_fma_f32 v[18:19], v[72:73], v[58:59], v[18:19] op_sel:[0,1,0] op_sel_hi:[1,1,1]
	v_pk_fma_f32 v[20:21], v[72:73], v[56:57], v[20:21] op_sel:[0,1,0] op_sel_hi:[1,1,1]
	v_pk_fma_f32 v[22:23], v[72:73], v[54:55], v[22:23] op_sel:[0,1,0] op_sel_hi:[1,1,1]
	v_pk_fma_f32 v[24:25], v[72:73], v[52:53], v[24:25] op_sel:[0,1,0] op_sel_hi:[1,1,1]
	v_pk_fma_f32 v[26:27], v[72:73], v[50:51], v[26:27] op_sel:[0,1,0] op_sel_hi:[1,1,1]
	v_pk_fma_f32 v[28:29], v[72:73], v[48:49], v[28:29] op_sel:[0,1,0] op_sel_hi:[1,1,1]
	v_pk_fma_f32 v[30:31], v[72:73], v[46:47], v[30:31] op_sel:[0,1,0] op_sel_hi:[1,1,1]
	ds_read2st64_b32 v[88:89], v96 offset0:208 offset1:212
	s_waitcnt lgkmcnt(6)
	v_pk_fma_f32 v[16:17], v[74:75], v[62:63], v[16:17] op_sel_hi:[1,0,1]
	v_pk_fma_f32 v[18:19], v[74:75], v[60:61], v[18:19] op_sel_hi:[1,0,1]
	v_pk_fma_f32 v[20:21], v[74:75], v[58:59], v[20:21] op_sel_hi:[1,0,1]
	v_pk_fma_f32 v[22:23], v[74:75], v[56:57], v[22:23] op_sel_hi:[1,0,1]
	v_pk_fma_f32 v[24:25], v[74:75], v[54:55], v[24:25] op_sel_hi:[1,0,1]
	v_pk_fma_f32 v[26:27], v[74:75], v[52:53], v[26:27] op_sel_hi:[1,0,1]
	v_pk_fma_f32 v[28:29], v[74:75], v[50:51], v[28:29] op_sel_hi:[1,0,1]
	v_pk_fma_f32 v[30:31], v[74:75], v[48:49], v[30:31] op_sel_hi:[1,0,1]
	ds_read2st64_b32 v[90:91], v96 offset0:212 offset1:216
	s_waitcnt lgkmcnt(6)
; __device__ __forceinline__ void conv_unit(Ctx& F, const bf16* P, bf16* O, int seq_row0, int seq_len, int t0, const float* wdw, const float* bdw, const float* lng, const float* lnb) {
;     ...
;     for (int tt = 0; tt < 32; ++tt) { float a = bb; const float* yp = y + (hf * 32 + tt) * 256 + c;
; #pragma unroll
;         for (int k = 0; k < 31; ++k) a += w[k] * yp[k * 256];
;         outv[tt] = a; }
;     __syncthreads();
; #pragma unroll
;     for (int tt = 0; tt < 32; ++tt) y[(hf * 32 + tt) * 256 + c] = outv[tt];
;     __syncthreads();
;     const int lane = F.lane, wave = F.wave;
;     const f32x4 gg = *(const f32x4*)(lng + 4 * lane), be = *(const f32x4*)(lnb + 4 * lane);
	v_pk_fma_f32 v[18:19], v[76:77], v[60:61], v[18:19] op_sel:[0,1,0] op_sel_hi:[1,1,1]
	v_pk_fma_f32 v[20:21], v[76:77], v[58:59], v[20:21] op_sel:[0,1,0] op_sel_hi:[1,1,1]
	v_pk_fma_f32 v[22:23], v[76:77], v[56:57], v[22:23] op_sel:[0,1,0] op_sel_hi:[1,1,1]
	v_pk_fma_f32 v[24:25], v[76:77], v[54:55], v[24:25] op_sel:[0,1,0] op_sel_hi:[1,1,1]
	v_pk_fma_f32 v[26:27], v[76:77], v[52:53], v[26:27] op_sel:[0,1,0] op_sel_hi:[1,1,1]
	v_pk_fma_f32 v[28:29], v[76:77], v[50:51], v[28:29] op_sel:[0,1,0] op_sel_hi:[1,1,1]
	v_pk_fma_f32 v[30:31], v[76:77], v[48:49], v[30:31] op_sel:[0,1,0] op_sel_hi:[1,1,1]
	ds_read2st64_b32 v[92:93], v96 offset0:216 offset1:220
	s_waitcnt lgkmcnt(6)
	v_pk_fma_f32 v[18:19], v[78:79], v[62:63], v[18:19] op_sel_hi:[1,0,1]
	v_pk_fma_f32 v[20:21], v[78:79], v[60:61], v[20:21] op_sel_hi:[1,0,1]
	v_pk_fma_f32 v[22:23], v[78:79], v[58:59], v[22:23] op_sel_hi:[1,0,1]
	v_pk_fma_f32 v[24:25], v[78:79], v[56:57], v[24:25] op_sel_hi:[1,0,1]
	v_pk_fma_f32 v[26:27], v[78:79], v[54:55], v[26:27] op_sel_hi:[1,0,1]
	v_pk_fma_f32 v[28:29], v[78:79], v[52:53], v[28:29] op_sel_hi:[1,0,1]
	v_pk_fma_f32 v[30:31], v[78:79], v[50:51], v[30:31] op_sel_hi:[1,0,1]
	ds_read2st64_b32 v[94:95], v96 offset0:220 offset1:224
	s_waitcnt lgkmcnt(6)
	v_pk_fma_f32 v[20:21], v[82:83], v[60:61], v[20:21] op_sel:[0,1,0] op_sel_hi:[1,1,1]
	v_pk_fma_f32 v[22:23], v[82:83], v[58:59], v[22:23] op_sel:[0,1,0] op_sel_hi:[1,1,1]
	v_pk_fma_f32 v[24:25], v[82:83], v[56:57], v[24:25] op_sel:[0,1,0] op_sel_hi:[1,1,1]
	v_pk_fma_f32 v[26:27], v[82:83], v[54:55], v[26:27] op_sel:[0,1,0] op_sel_hi:[1,1,1]
	v_pk_fma_f32 v[28:29], v[82:83], v[52:53], v[28:29] op_sel:[0,1,0] op_sel_hi:[1,1,1]
	v_pk_fma_f32 v[30:31], v[82:83], v[50:51], v[30:31] op_sel:[0,1,0] op_sel_hi:[1,1,1]
	ds_read2st64_b32 v[66:67], v96 offset0:224 offset1:228
	s_waitcnt lgkmcnt(6)
	v_pk_fma_f32 v[20:21], v[84:85], v[62:63], v[20:21] op_sel_hi:[1,0,1]
	v_pk_fma_f32 v[22:23], v[84:85], v[60:61], v[22:23] op_sel_hi:[1,0,1]
	v_pk_fma_f32 v[24:25], v[84:85], v[58:59], v[24:25] op_sel_hi:[1,0,1]
	v_pk_fma_f32 v[26:27], v[84:85], v[56:57], v[26:27] op_sel_hi:[1,0,1]
	v_pk_fma_f32 v[28:29], v[84:85], v[54:55], v[28:29] op_sel_hi:[1,0,1]
	v_pk_fma_f32 v[30:31], v[84:85], v[52:53], v[30:31] op_sel_hi:[1,0,1]
	ds_read2st64_b32 v[68:69], v96 offset0:228 offset1:232
	s_waitcnt lgkmcnt(6)
	v_pk_fma_f32 v[22:23], v[86:87], v[60:61], v[22:23] op_sel:[0,1,0] op_sel_hi:[1,1,1]
	v_pk_fma_f32 v[24:25], v[86:87], v[58:59], v[24:25] op_sel:[0,1,0] op_sel_hi:[1,1,1]
	v_pk_fma_f32 v[26:27], v[86:87], v[56:57], v[26:27] op_sel:[0,1,0] op_sel_hi:[1,1,1]
	v_pk_fma_f32 v[28:29], v[86:87], v[54:55], v[28:29] op_sel:[0,1,0] op_sel_hi:[1,1,1]
	v_pk_fma_f32 v[30:31], v[86:87], v[52:53], v[30:31] op_sel:[0,1,0] op_sel_hi:[1,1,1]
	ds_read2st64_b32 v[70:71], v96 offset0:232 offset1:236
	s_waitcnt lgkmcnt(6)
	v_pk_fma_f32 v[22:23], v[88:89], v[62:63], v[22:23] op_sel_hi:[1,0,1]
	v_pk_fma_f32 v[24:25], v[88:89], v[60:61], v[24:25] op_sel_hi:[1,0,1]
	v_pk_fma_f32 v[26:27], v[88:89], v[58:59], v[26:27] op_sel_hi:[1,0,1]
	v_pk_fma_f32 v[28:29], v[88:89], v[56:57], v[28:29] op_sel_hi:[1,0,1]
	v_pk_fma_f32 v[30:31], v[88:89], v[54:55], v[30:31] op_sel_hi:[1,0,1]
	ds_read2st64_b32 v[72:73], v96 offset0:236 offset1:240
	s_waitcnt lgkmcnt(6)
	v_pk_fma_f32 v[24:25], v[90:91], v[60:61], v[24:25] op_sel:[0,1,0] op_sel_hi:[1,1,1]
	v_pk_fma_f32 v[26:27], v[90:91], v[58:59], v[26:27] op_sel:[0,1,0] op_sel_hi:[1,1,1]
	v_pk_fma_f32 v[28:29], v[90:91], v[56:57], v[28:29] op_sel:[0,1,0] op_sel_hi:[1,1,1]
	v_pk_fma_f32 v[30:31], v[90:91], v[54:55], v[30:31] op_sel:[0,1,0] op_sel_hi:[1,1,1]
	ds_read2st64_b32 v[74:75], v96 offset0:240 offset1:244
	s_waitcnt lgkmcnt(6)
	v_pk_fma_f32 v[24:25], v[92:93], v[62:63], v[24:25] op_sel_hi:[1,0,1]
	v_pk_fma_f32 v[26:27], v[92:93], v[60:61], v[26:27] op_sel_hi:[1,0,1]
	v_pk_fma_f32 v[28:29], v[92:93], v[58:59], v[28:29] op_sel_hi:[1,0,1]
	v_pk_fma_f32 v[30:31], v[92:93], v[56:57], v[30:31] op_sel_hi:[1,0,1]
	s_waitcnt lgkmcnt(5)
	v_pk_fma_f32 v[26:27], v[94:95], v[60:61], v[26:27] op_sel:[0,1,0] op_sel_hi:[1,1,1]
	v_pk_fma_f32 v[28:29], v[94:95], v[58:59], v[28:29] op_sel:[0,1,0] op_sel_hi:[1,1,1]
	v_pk_fma_f32 v[30:31], v[94:95], v[56:57], v[30:31] op_sel:[0,1,0] op_sel_hi:[1,1,1]
	s_waitcnt lgkmcnt(4)
	v_pk_fma_f32 v[26:27], v[66:67], v[62:63], v[26:27] op_sel_hi:[1,0,1]
	v_pk_fma_f32 v[28:29], v[66:67], v[60:61], v[28:29] op_sel_hi:[1,0,1]
	v_pk_fma_f32 v[30:31], v[66:67], v[58:59], v[30:31] op_sel_hi:[1,0,1]
	s_waitcnt lgkmcnt(3)
	v_pk_fma_f32 v[28:29], v[68:69], v[60:61], v[28:29] op_sel:[0,1,0] op_sel_hi:[1,1,1]
	v_pk_fma_f32 v[30:31], v[68:69], v[58:59], v[30:31] op_sel:[0,1,0] op_sel_hi:[1,1,1]
	s_waitcnt lgkmcnt(2)
	v_pk_fma_f32 v[28:29], v[70:71], v[62:63], v[28:29] op_sel_hi:[1,0,1]
	v_pk_fma_f32 v[30:31], v[70:71], v[60:61], v[30:31] op_sel_hi:[1,0,1]
	s_waitcnt lgkmcnt(1)
	v_pk_fma_f32 v[30:31], v[72:73], v[60:61], v[30:31] op_sel:[0,1,0] op_sel_hi:[1,1,1]
	s_waitcnt lgkmcnt(0)
	v_pk_fma_f32 v[30:31], v[74:75], v[62:63], v[30:31] op_sel_hi:[1,0,1]
	s_barrier
	ds_write2st64_b32 v96, v0, v1 offset1:4
	ds_write2st64_b32 v96, v2, v3 offset0:8 offset1:12
	ds_write2st64_b32 v96, v4, v5 offset0:16 offset1:20
	ds_write2st64_b32 v96, v6, v7 offset0:24 offset1:28
	ds_write2st64_b32 v96, v8, v9 offset0:32 offset1:36
	ds_write2st64_b32 v96, v10, v11 offset0:40 offset1:44
	ds_write2st64_b32 v96, v12, v13 offset0:48 offset1:52
	ds_write2st64_b32 v96, v14, v15 offset0:56 offset1:60
	ds_write2st64_b32 v96, v16, v17 offset0:64 offset1:68
	ds_write2st64_b32 v96, v18, v19 offset0:72 offset1:76
	ds_write2st64_b32 v96, v20, v21 offset0:80 offset1:84
	ds_write2st64_b32 v96, v22, v23 offset0:88 offset1:92
	ds_write2st64_b32 v96, v24, v25 offset0:96 offset1:100
	ds_write2st64_b32 v96, v26, v27 offset0:104 offset1:108
	ds_write2st64_b32 v96, v28, v29 offset0:112 offset1:116
	ds_write2st64_b32 v96, v30, v31 offset0:120 offset1:124
	v_lshlrev_b32_e32 v0, 4, v80
	v_and_b32_e32 v4, 0x3f0, v0
	s_waitcnt lgkmcnt(0)
	s_barrier
	global_load_dwordx4 v[0:3], v4, s[20:21]
	s_nop 0
	global_load_dwordx4 v[4:7], v4, s[22:23]
	v_cndmask_b32_e32 v8, v235, v237, vcc
	v_cmp_lt_i32_e32 vcc, v254, v236
	v_lshlrev_b32_e32 v10, 2, v8
	s_nop 0
	v_cndmask_b32_e32 v8, v235, v254, vcc
	v_cmp_lt_i32_e32 vcc, v247, v236
	v_lshlrev_b32_e32 v11, 2, v8
	s_nop 0
	v_cndmask_b32_e32 v8, v235, v247, vcc
	v_cmp_lt_i32_e32 vcc, v249, v236
	v_lshlrev_b32_e32 v12, 2, v8
	s_nop 0
	v_cndmask_b32_e32 v8, v235, v249, vcc
	v_cmp_lt_i32_e32 vcc, v250, v236
	v_lshlrev_b32_e32 v13, 2, v8
	s_nop 0
	v_cndmask_b32_e32 v8, v235, v250, vcc
	v_cmp_lt_i32_e32 vcc, v242, v236
	v_lshlrev_b32_e32 v14, 2, v8
	s_nop 0
	v_cndmask_b32_e32 v8, v235, v242, vcc
	v_lshlrev_b32_e32 v15, 2, v8
	v_and_b32_e32 v8, 63, v80
	v_lshlrev_b32_e32 v204, 3, v8
	v_lshl_add_u32 v16, v8, 4, s3
	v_lshl_add_u64 v[8:9], s[0:1], 0, v[204:205]
	s_waitcnt vmcnt(0)
